# attention: lane^32 exchanges via v_permlane32_swap instead of ds_bpermute round trips
# baseline (speedup 1.0000x reference)
.LBB0_251:
	v_and_b32_e32 v50, 64, v205
	v_xor_b32_e32 v0, 32, v205
	v_add_u32_e32 v50, 64, v50
	v_cmp_lt_i32_e32 vcc, v0, v50
	v_mov_b32_e32 v50, v5
	v_mov_b32_e32 v51, v2
	v_mov_b32_e32 v52, v48
	v_mov_b32_e32 v53, v3
	v_pk_add_f32 v[50:51], v[50:51], v[52:53]
	v_mov_b32_e32 v52, v7
	v_mov_b32_e32 v53, v6
	v_mov_b32_e32 v54, v4
	v_mov_b32_e32 v55, v49
	v_pk_add_f32 v[52:53], v[52:53], v[54:55]
	v_mov_b32_e32 v54, v9
	v_mov_b32_e32 v55, v10
	v_mov_b32_e32 v56, v8
	v_mov_b32_e32 v57, v11
	v_pk_add_f32 v[54:55], v[54:55], v[56:57]
	v_mov_b32_e32 v56, v13
	v_mov_b32_e32 v57, v14
	v_mov_b32_e32 v58, v12
	v_mov_b32_e32 v59, v15
	v_cndmask_b32_e32 v0, v205, v0, vcc
	v_pk_add_f32 v[56:57], v[56:57], v[58:59]
	v_lshlrev_b32_e32 v60, 2, v0
	v_pk_add_f32 v[56:57], v[56:57], v[56:57] op_sel:[0,1] op_sel_hi:[1,0]
	v_mov_b32_e32 v251, v56
	v_mov_b32_e32 v57, v56
	s_nop 1
	v_permlane32_swap_b32_e32 v57, v251
	v_cndmask_b32_e64 v57, v57, v251, s[42:43]
	v_mov_b32_e32 v58, v54
	v_mov_b32_e32 v59, v56
	v_mov_b32_e32 v56, v55
	v_add_f32_e32 v50, v50, v51
	s_waitcnt lgkmcnt(0)
	v_add_f32_e32 v0, 0, v57
	v_pk_add_f32 v[54:55], v[58:59], v[56:57]
	v_cndmask_b32_e64 v61, 0, v0, s[42:43]
	v_mov_b32_e32 v251, v54
	v_mov_b32_e32 v0, v54
	s_nop 1
	v_permlane32_swap_b32_e32 v0, v251
	v_cndmask_b32_e64 v0, v0, v251, s[42:43]
	v_mov_b32_e32 v251, v50
	v_mov_b32_e32 v51, v50
	s_nop 1
	v_permlane32_swap_b32_e32 v51, v251
	v_cndmask_b32_e64 v51, v51, v251, s[42:43]
	s_and_b64 vcc, exec, s[0:1]
	s_waitcnt lgkmcnt(1)
	v_cndmask_b32_e64 v56, 0, v0, s[42:43]
	v_pk_add_f32 v[54:55], v[54:55], v[0:1]
	s_nop 0
	v_add_f32_e32 v58, v56, v55
	v_mov_b32_e32 v56, v52
	v_mov_b32_e32 v57, v54
	v_mov_b32_e32 v54, v53
	v_pk_add_f32 v[52:53], v[56:57], v[54:55]
	v_mov_b32_e32 v251, v52
	v_mov_b32_e32 v0, v52
	s_nop 1
	v_permlane32_swap_b32_e32 v0, v251
	v_cndmask_b32_e64 v0, v0, v251, s[42:43]
	s_waitcnt lgkmcnt(0)
	v_cndmask_b32_e64 v54, 0, v0, s[42:43]
	v_add_f32_e32 v0, v52, v0
	v_add_f32_e32 v52, v0, v53
	v_cndmask_b32_e64 v0, 0, v51, s[42:43]
	v_add_f32_e32 v0, v0, v52
	v_add_f32_e32 v0, v3, v0
	v_add_f32_e32 v3, v35, v0
	v_add_f32_e32 v0, v2, v0
	v_add_f32_e32 v2, v34, v0
	v_add_f32_e32 v0, v5, v0
	v_add_f32_e32 v54, v54, v53
	v_add_f32_e32 v5, v33, v0
	v_add_f32_e32 v0, v48, v0
	v_add_f32_e32 v0, v32, v0
	v_add_f32_e32 v32, v49, v54
	v_add_f32_e32 v33, v39, v32
	v_add_f32_e32 v32, v6, v32
	v_add_f32_e32 v6, v38, v32
	v_add_f32_e32 v32, v7, v32
	v_add_f32_e32 v7, v37, v32
	v_add_f32_e32 v4, v4, v32
	v_add_f32_e32 v32, v11, v58
	v_add_f32_e32 v11, v43, v32
	v_add_f32_e32 v32, v10, v32
	v_add_f32_e32 v10, v42, v32
	v_add_f32_e32 v32, v9, v32
	v_add_f32_e32 v9, v41, v32
	v_add_f32_e32 v8, v8, v32
	v_add_f32_e32 v32, v15, v61
	v_add_f32_e32 v15, v47, v32
	v_add_f32_e32 v32, v14, v32
	v_add_f32_e32 v14, v46, v32
	v_add_f32_e32 v32, v13, v32
	v_add_f32_e32 v12, v12, v32
	v_add_f32_e32 v4, v36, v4
	v_add_f32_e32 v8, v40, v8
	v_add_f32_e32 v13, v45, v32
	v_add_f32_e32 v12, v44, v12
	v_exp_f32_e32 v3, v3
	v_exp_f32_e32 v2, v2
	v_exp_f32_e32 v5, v5
	v_exp_f32_e32 v0, v0
	v_exp_f32_e32 v33, v33
	v_exp_f32_e32 v6, v6
	v_exp_f32_e32 v7, v7
	v_exp_f32_e32 v4, v4
	v_exp_f32_e32 v11, v11
	v_exp_f32_e32 v10, v10
	v_exp_f32_e32 v9, v9
	v_exp_f32_e32 v8, v8
	v_exp_f32_e32 v15, v15
	v_exp_f32_e32 v14, v14
	v_exp_f32_e32 v13, v13
	v_exp_f32_e32 v12, v12
	s_cbranch_vccnz .LBB0_253
	v_cndmask_b32_e64 v0, 0, v0, s[6:7]
	v_cndmask_b32_e64 v5, 0, v5, s[8:9]
	v_cndmask_b32_e64 v2, 0, v2, s[10:11]
	v_cndmask_b32_e64 v3, 0, v3, s[12:13]
	v_cndmask_b32_e64 v4, 0, v4, s[14:15]
	v_cndmask_b32_e64 v7, 0, v7, s[16:17]
	v_cndmask_b32_e64 v6, 0, v6, s[18:19]
	v_cndmask_b32_e64 v33, 0, v33, s[20:21]
	v_cndmask_b32_e64 v8, 0, v8, s[22:23]
	v_cndmask_b32_e64 v9, 0, v9, s[24:25]
	v_cndmask_b32_e64 v10, 0, v10, s[26:27]
	v_cndmask_b32_e64 v11, 0, v11, s[28:29]
	v_cndmask_b32_e64 v12, 0, v12, s[30:31]
	v_cndmask_b32_e64 v13, 0, v13, s[34:35]
	v_cndmask_b32_e64 v14, 0, v14, s[36:37]
	v_cndmask_b32_e64 v15, 0, v15, s[38:39]

.LBB0_257:
	v_and_b32_e32 v2, 64, v205
	v_xor_b32_e32 v0, 32, v205
	v_add_u32_e32 v2, 64, v2
	v_cmp_lt_i32_e32 vcc, v0, v2
	v_pk_add_f32 v[2:3], v[112:113], v[14:15]
	v_pk_add_f32 v[228:229], v[176:177], v[8:9]
	v_cndmask_b32_e32 v0, v205, v0, vcc
	v_lshlrev_b32_e32 v236, 2, v0
	v_pk_add_f32 v[2:3], v[2:3], v[2:3] op_sel:[0,1] op_sel_hi:[1,0]
	v_mov_b32_e32 v251, v2
	v_mov_b32_e32 v3, v2
	s_nop 1
	v_permlane32_swap_b32_e32 v3, v251
	v_cndmask_b32_e64 v3, v3, v251, s[42:43]
	v_mov_b32_e32 v230, v228
	v_mov_b32_e32 v231, v2
	v_mov_b32_e32 v2, v229
	v_pk_add_f32 v[232:233], v[12:13], v[10:11]
	s_waitcnt lgkmcnt(0)
	v_pk_add_f32 v[230:231], v[230:231], v[2:3]
	v_mov_b32_e32 v251, v230
	v_mov_b32_e32 v0, v230
	s_nop 1
	v_permlane32_swap_b32_e32 v0, v251
	v_cndmask_b32_e64 v0, v0, v251, s[42:43]
	v_mov_b32_e32 v234, v232
	v_pk_add_f32 v[228:229], v[6:7], v[4:5]
	v_add_f32_e32 v3, 0, v3
	v_add_f32_e32 v228, v228, v229
	s_waitcnt lgkmcnt(0)
	v_pk_add_f32 v[230:231], v[230:231], v[0:1]
	v_mov_b32_e32 v251, v228
	v_mov_b32_e32 v229, v228
	s_nop 1
	v_permlane32_swap_b32_e32 v229, v251
	v_cndmask_b32_e64 v229, v229, v251, s[42:43]
	v_mov_b32_e32 v235, v230
	v_mov_b32_e32 v230, v233
	v_pk_add_f32 v[232:233], v[234:235], v[230:231]
	v_mov_b32_e32 v251, v232
	v_mov_b32_e32 v2, v232
	s_nop 1
	v_permlane32_swap_b32_e32 v2, v251
	v_cndmask_b32_e64 v2, v2, v251, s[42:43]
	v_cndmask_b32_e64 v0, 0, v0, s[42:43]
	v_add_f32_e32 v231, v0, v231
	v_cndmask_b32_e64 v234, 0, v3, s[42:43]
	s_and_b64 vcc, exec, s[0:1]
	s_waitcnt lgkmcnt(0)
	v_cndmask_b32_e64 v0, 0, v2, s[42:43]
	v_add_f32_e32 v235, v0, v233
	v_add_f32_e32 v0, v232, v2
	v_add_f32_e32 v230, v0, v233
	v_cndmask_b32_e64 v0, 0, v229, s[42:43]
	v_add_f32_e32 v0, v0, v230
	v_add_f32_e32 v0, v227, v0
	v_add_f32_e32 v0, v5, v0
	v_add_f32_e32 v2, v99, v0
	v_add_f32_e32 v0, v7, v0
	v_exp_f32_e32 v3, v2
	v_add_f32_e32 v2, v98, v0
	v_add_f32_e32 v0, v6, v0
	v_add_f32_e32 v5, v97, v0
	v_add_f32_e32 v0, v4, v0
	v_add_f32_e32 v4, v227, v235
	v_add_f32_e32 v4, v11, v4
	v_add_f32_e32 v6, v103, v4
	v_add_f32_e32 v4, v13, v4
	v_exp_f32_e32 v7, v6
	v_add_f32_e32 v6, v102, v4
	v_add_f32_e32 v4, v12, v4
	v_add_f32_e32 v11, v101, v4
	v_add_f32_e32 v4, v10, v4
	v_add_f32_e32 v10, v227, v231
	v_add_f32_e32 v9, v9, v10
	v_add_f32_e32 v10, v107, v9
	v_add_f32_e32 v9, v177, v9
	v_add_f32_e32 v12, v176, v9
	v_exp_f32_e32 v13, v11
	v_exp_f32_e32 v11, v10
	v_add_f32_e32 v10, v106, v9
	v_add_f32_e32 v9, v105, v12
	v_add_f32_e32 v8, v8, v12
	v_add_f32_e32 v12, v227, v234
	v_add_f32_e32 v12, v15, v12
	v_add_f32_e32 v15, v111, v12
	v_add_f32_e32 v12, v113, v12
	v_add_f32_e32 v0, v96, v0
	v_add_f32_e32 v96, v110, v12
	v_add_f32_e32 v12, v112, v12
	v_add_f32_e32 v97, v109, v12
	v_add_f32_e32 v12, v14, v12
	v_add_f32_e32 v4, v100, v4
	v_add_f32_e32 v8, v104, v8
	v_add_f32_e32 v12, v108, v12
	v_exp_f32_e32 v2, v2
	v_exp_f32_e32 v5, v5
	v_exp_f32_e32 v0, v0
	v_exp_f32_e32 v6, v6
	v_exp_f32_e32 v4, v4
	v_exp_f32_e32 v10, v10
	v_exp_f32_e32 v9, v9
	v_exp_f32_e32 v8, v8
	v_exp_f32_e32 v15, v15
	v_exp_f32_e32 v14, v96
	v_exp_f32_e32 v97, v97
	v_exp_f32_e32 v12, v12
	s_cbranch_vccnz .LBB0_259
	v_cndmask_b32_e64 v0, 0, v0, s[6:7]
	v_cndmask_b32_e64 v5, 0, v5, s[8:9]
	v_cndmask_b32_e64 v2, 0, v2, s[10:11]
	v_cndmask_b32_e64 v3, 0, v3, s[12:13]
	v_cndmask_b32_e64 v4, 0, v4, s[14:15]
	v_cndmask_b32_e64 v13, 0, v13, s[16:17]
	v_cndmask_b32_e64 v6, 0, v6, s[18:19]
	v_cndmask_b32_e64 v7, 0, v7, s[20:21]
	v_cndmask_b32_e64 v8, 0, v8, s[22:23]
	v_cndmask_b32_e64 v9, 0, v9, s[24:25]
	v_cndmask_b32_e64 v10, 0, v10, s[26:27]
	v_cndmask_b32_e64 v11, 0, v11, s[28:29]
	v_cndmask_b32_e64 v12, 0, v12, s[30:31]
	v_cndmask_b32_e64 v97, 0, v97, s[34:35]
	v_cndmask_b32_e64 v14, 0, v14, s[36:37]
	v_cndmask_b32_e64 v15, 0, v15, s[38:39]

.LBB0_279:
	v_mov_b32_e32 v238, v5
	v_mov_b32_e32 v239, v2
	v_mov_b32_e32 v240, v112
	v_mov_b32_e32 v241, v3
	v_and_b32_e32 v177, 64, v205
	v_pk_add_f32 v[238:239], v[238:239], v[240:241]
	v_mov_b32_e32 v240, v7
	v_mov_b32_e32 v241, v6
	v_mov_b32_e32 v242, v4
	v_mov_b32_e32 v243, v113
	v_xor_b32_e32 v0, 32, v205
	v_add_u32_e32 v177, 64, v177
	v_pk_add_f32 v[240:241], v[240:241], v[242:243]
	v_mov_b32_e32 v242, v9
	v_mov_b32_e32 v243, v10
	v_mov_b32_e32 v244, v8
	v_mov_b32_e32 v245, v11
	v_cmp_lt_i32_e32 vcc, v0, v177
	v_pk_add_f32 v[242:243], v[242:243], v[244:245]
	v_mov_b32_e32 v244, v13
	v_mov_b32_e32 v245, v14
	v_mov_b32_e32 v246, v12
	v_mov_b32_e32 v247, v15
	v_cndmask_b32_e32 v0, v205, v0, vcc
	v_pk_add_f32 v[244:245], v[244:245], v[246:247]
	v_lshlrev_b32_e32 v248, 2, v0
	v_pk_add_f32 v[244:245], v[244:245], v[244:245] op_sel:[0,1] op_sel_hi:[1,0]
	v_mov_b32_e32 v251, v244
	v_mov_b32_e32 v245, v244
	s_nop 1
	v_permlane32_swap_b32_e32 v245, v251
	v_cndmask_b32_e64 v245, v245, v251, s[42:43]
	v_mov_b32_e32 v246, v242
	v_mov_b32_e32 v247, v244
	v_mov_b32_e32 v244, v243
	v_add_f32_e32 v177, v238, v239
	s_waitcnt lgkmcnt(0)
	v_add_f32_e32 v0, 0, v245
	v_pk_add_f32 v[242:243], v[246:247], v[244:245]
	v_cndmask_b32_e64 v249, 0, v0, s[42:43]
	v_mov_b32_e32 v251, v242
	v_mov_b32_e32 v0, v242
	s_nop 1
	v_permlane32_swap_b32_e32 v0, v251
	v_cndmask_b32_e64 v0, v0, v251, s[42:43]
	v_mov_b32_e32 v244, v240
	v_mov_b32_e32 v251, v177
	v_mov_b32_e32 v238, v177
	s_nop 1
	v_permlane32_swap_b32_e32 v238, v251
	v_cndmask_b32_e64 v238, v238, v251, s[42:43]
	s_andn2_b64 vcc, exec, s[64:65]
	s_waitcnt lgkmcnt(1)
	v_pk_add_f32 v[242:243], v[242:243], v[0:1]
	s_nop 0
	v_mov_b32_e32 v245, v242
	v_mov_b32_e32 v242, v241
	v_pk_add_f32 v[240:241], v[244:245], v[242:243]
	v_cndmask_b32_e64 v239, 0, v0, s[42:43]
	v_mov_b32_e32 v251, v240
	v_mov_b32_e32 v0, v240
	s_nop 1
	v_permlane32_swap_b32_e32 v0, v251
	v_cndmask_b32_e64 v0, v0, v251, s[42:43]
	v_add_f32_e32 v246, v239, v243
	s_waitcnt lgkmcnt(0)
	v_cndmask_b32_e64 v239, 0, v0, s[42:43]
	v_add_f32_e32 v0, v240, v0
	v_add_f32_e32 v242, v239, v241
	v_add_f32_e32 v239, v0, v241
	v_cndmask_b32_e64 v0, 0, v238, s[42:43]
	v_add_f32_e32 v0, v0, v239
	v_add_f32_e32 v0, v227, v0
	v_add_f32_e32 v0, v3, v0
	v_add_f32_e32 v3, v99, v0
	v_add_f32_e32 v0, v2, v0
	v_add_f32_e32 v2, v98, v0
	v_add_f32_e32 v0, v5, v0
	v_add_f32_e32 v5, v97, v0
	v_add_f32_e32 v0, v112, v0
	v_add_f32_e32 v0, v96, v0
	v_add_f32_e32 v96, v227, v242
	v_add_f32_e32 v96, v113, v96
	v_add_f32_e32 v97, v103, v96
	v_add_f32_e32 v96, v6, v96
	v_add_f32_e32 v6, v102, v96
	v_add_f32_e32 v96, v7, v96
	v_add_f32_e32 v7, v101, v96
	v_add_f32_e32 v4, v4, v96
	v_add_f32_e32 v96, v227, v246
	v_add_f32_e32 v96, v11, v96
	v_add_f32_e32 v11, v107, v96
	v_add_f32_e32 v96, v10, v96
	v_add_f32_e32 v10, v106, v96
	v_add_f32_e32 v96, v9, v96
	v_add_f32_e32 v9, v105, v96
	v_add_f32_e32 v8, v8, v96
	v_add_f32_e32 v96, v227, v249
	v_add_f32_e32 v96, v15, v96
	v_add_f32_e32 v15, v111, v96
	v_add_f32_e32 v96, v14, v96
	v_add_f32_e32 v14, v110, v96
	v_add_f32_e32 v96, v13, v96
	v_add_f32_e32 v12, v12, v96
	v_add_f32_e32 v4, v100, v4
	v_add_f32_e32 v8, v104, v8
	v_add_f32_e32 v13, v109, v96
	v_add_f32_e32 v12, v108, v12
	v_exp_f32_e32 v3, v3
	v_exp_f32_e32 v2, v2
	v_exp_f32_e32 v5, v5
	v_exp_f32_e32 v0, v0
	v_exp_f32_e32 v97, v97
	v_exp_f32_e32 v6, v6
	v_exp_f32_e32 v7, v7
	v_exp_f32_e32 v4, v4
	v_exp_f32_e32 v11, v11
	v_exp_f32_e32 v10, v10
	v_exp_f32_e32 v9, v9
	v_exp_f32_e32 v8, v8
	v_exp_f32_e32 v15, v15
	v_exp_f32_e32 v14, v14
	v_exp_f32_e32 v13, v13
	v_exp_f32_e32 v12, v12
	s_cbranch_vccnz .LBB0_281
	v_cndmask_b32_e64 v0, 0, v0, s[6:7]
	v_cndmask_b32_e64 v5, 0, v5, s[8:9]
	v_cndmask_b32_e64 v2, 0, v2, s[10:11]
	v_cndmask_b32_e64 v3, 0, v3, s[12:13]
	v_cndmask_b32_e64 v4, 0, v4, s[14:15]
	v_cndmask_b32_e64 v7, 0, v7, s[16:17]
	v_cndmask_b32_e64 v6, 0, v6, s[18:19]
	v_cndmask_b32_e64 v97, 0, v97, s[20:21]
	v_cndmask_b32_e64 v8, 0, v8, s[22:23]
	v_cndmask_b32_e64 v9, 0, v9, s[24:25]
	v_cndmask_b32_e64 v10, 0, v10, s[26:27]
	v_cndmask_b32_e64 v11, 0, v11, s[28:29]
	v_cndmask_b32_e64 v12, 0, v12, s[30:31]
	v_cndmask_b32_e64 v13, 0, v13, s[34:35]
	v_cndmask_b32_e64 v14, 0, v14, s[36:37]
	v_cndmask_b32_e64 v15, 0, v15, s[38:39]

.LBB0_285:
	v_and_b32_e32 v2, 64, v205
	v_xor_b32_e32 v0, 32, v205
	v_add_u32_e32 v2, 64, v2
	v_cmp_lt_i32_e32 vcc, v0, v2
	v_pk_add_f32 v[2:3], v[112:113], v[14:15]
	v_pk_add_f32 v[238:239], v[176:177], v[8:9]
	v_cndmask_b32_e32 v0, v205, v0, vcc
	v_lshlrev_b32_e32 v246, 2, v0
	v_pk_add_f32 v[2:3], v[2:3], v[2:3] op_sel:[0,1] op_sel_hi:[1,0]
	v_mov_b32_e32 v251, v2
	v_mov_b32_e32 v3, v2
	s_nop 1
	v_permlane32_swap_b32_e32 v3, v251
	v_cndmask_b32_e64 v3, v3, v251, s[42:43]
	v_mov_b32_e32 v240, v238
	v_mov_b32_e32 v241, v2
	v_mov_b32_e32 v2, v239
	v_pk_add_f32 v[242:243], v[12:13], v[10:11]
	s_waitcnt lgkmcnt(0)
	v_pk_add_f32 v[240:241], v[240:241], v[2:3]
	v_mov_b32_e32 v251, v240
	v_mov_b32_e32 v0, v240
	s_nop 1
	v_permlane32_swap_b32_e32 v0, v251
	v_cndmask_b32_e64 v0, v0, v251, s[42:43]
	v_mov_b32_e32 v244, v242
	v_pk_add_f32 v[238:239], v[6:7], v[4:5]
	v_add_f32_e32 v3, 0, v3
	v_add_f32_e32 v238, v238, v239
	s_waitcnt lgkmcnt(0)
	v_pk_add_f32 v[240:241], v[240:241], v[0:1]
	v_mov_b32_e32 v251, v238
	v_mov_b32_e32 v239, v238
	s_nop 1
	v_permlane32_swap_b32_e32 v239, v251
	v_cndmask_b32_e64 v239, v239, v251, s[42:43]
	v_mov_b32_e32 v245, v240
	v_mov_b32_e32 v240, v243
	v_pk_add_f32 v[242:243], v[244:245], v[240:241]
	v_mov_b32_e32 v251, v242
	v_mov_b32_e32 v2, v242
	s_nop 1
	v_permlane32_swap_b32_e32 v2, v251
	v_cndmask_b32_e64 v2, v2, v251, s[42:43]
	v_cndmask_b32_e64 v0, 0, v0, s[42:43]
	v_add_f32_e32 v241, v0, v241
	v_cndmask_b32_e64 v244, 0, v3, s[42:43]
	s_andn2_b64 vcc, exec, s[64:65]
	s_waitcnt lgkmcnt(0)
	v_cndmask_b32_e64 v0, 0, v2, s[42:43]
	v_add_f32_e32 v245, v0, v243
	v_add_f32_e32 v0, v242, v2
	v_add_f32_e32 v240, v0, v243
	v_cndmask_b32_e64 v0, 0, v239, s[42:43]
	v_add_f32_e32 v0, v0, v240
	v_add_f32_e32 v0, v227, v0
	v_add_f32_e32 v0, v5, v0
	v_add_f32_e32 v2, v99, v0
	v_add_f32_e32 v0, v7, v0
	v_exp_f32_e32 v3, v2
	v_add_f32_e32 v2, v98, v0
	v_add_f32_e32 v0, v6, v0
	v_add_f32_e32 v5, v97, v0
	v_add_f32_e32 v0, v4, v0
	v_add_f32_e32 v4, v227, v245
	v_add_f32_e32 v4, v11, v4
	v_add_f32_e32 v6, v103, v4
	v_add_f32_e32 v4, v13, v4
	v_exp_f32_e32 v7, v6
	v_add_f32_e32 v6, v102, v4
	v_add_f32_e32 v4, v12, v4
	v_add_f32_e32 v11, v101, v4
	v_add_f32_e32 v4, v10, v4
	v_add_f32_e32 v10, v227, v241
	v_add_f32_e32 v9, v9, v10
	v_add_f32_e32 v10, v107, v9
	v_add_f32_e32 v9, v177, v9
	v_add_f32_e32 v12, v176, v9
	v_exp_f32_e32 v13, v11
	v_exp_f32_e32 v11, v10
	v_add_f32_e32 v10, v106, v9
	v_add_f32_e32 v9, v105, v12
	v_add_f32_e32 v8, v8, v12
	v_add_f32_e32 v12, v227, v244
	v_add_f32_e32 v12, v15, v12
	v_add_f32_e32 v15, v111, v12
	v_add_f32_e32 v12, v113, v12
	v_add_f32_e32 v0, v96, v0
	v_add_f32_e32 v96, v110, v12
	v_add_f32_e32 v12, v112, v12
	v_add_f32_e32 v97, v109, v12
	v_add_f32_e32 v12, v14, v12
	v_add_f32_e32 v4, v100, v4
	v_add_f32_e32 v8, v104, v8
	v_add_f32_e32 v12, v108, v12
	v_exp_f32_e32 v2, v2
	v_exp_f32_e32 v5, v5
	v_exp_f32_e32 v0, v0
	v_exp_f32_e32 v6, v6
	v_exp_f32_e32 v4, v4
	v_exp_f32_e32 v10, v10
	v_exp_f32_e32 v9, v9
	v_exp_f32_e32 v8, v8
	v_exp_f32_e32 v15, v15
	v_exp_f32_e32 v14, v96
	v_exp_f32_e32 v97, v97
	v_exp_f32_e32 v12, v12
	s_cbranch_vccnz .LBB0_287
	v_cndmask_b32_e64 v0, 0, v0, s[6:7]
	v_cndmask_b32_e64 v5, 0, v5, s[8:9]
	v_cndmask_b32_e64 v2, 0, v2, s[10:11]
	v_cndmask_b32_e64 v3, 0, v3, s[12:13]
	v_cndmask_b32_e64 v4, 0, v4, s[14:15]
	v_cndmask_b32_e64 v13, 0, v13, s[16:17]
	v_cndmask_b32_e64 v6, 0, v6, s[18:19]
	v_cndmask_b32_e64 v7, 0, v7, s[20:21]
	v_cndmask_b32_e64 v8, 0, v8, s[22:23]
	v_cndmask_b32_e64 v9, 0, v9, s[24:25]
	v_cndmask_b32_e64 v10, 0, v10, s[26:27]
	v_cndmask_b32_e64 v11, 0, v11, s[28:29]
	v_cndmask_b32_e64 v12, 0, v12, s[30:31]
	v_cndmask_b32_e64 v97, 0, v97, s[34:35]
	v_cndmask_b32_e64 v14, 0, v14, s[36:37]
	v_cndmask_b32_e64 v15, 0, v15, s[38:39]
